# rope phase: cross-row load pipelining, resident gain words, hoisted rope frequencies and wave-major worker index combined
# baseline (speedup 1.0000x reference)
.Lgb3_done:
.LBB0_989:
	s_or_b64 exec, exec, s[2:3]
	v_mov_b32_e32 v0, v214
	v_readlane_b32 s3, v253, 0
	s_waitcnt lgkmcnt(0)
	s_barrier
	s_lshl_b32 s3, s3, 3
	v_readfirstlane_b32 s2, v0
	s_ashr_i32 s2, s2, 6
	s_lshr_b32 s14, s88, 3
	s_mul_i32 s2, s2, s14
	s_lshr_b32 s3, s3, 3
	s_add_i32 s2, s2, s3
	s_cmpk_gt_i32 s2, 0x23ff
	s_cbranch_scc1 .LBB0_1012
	v_and_b32_e32 v58, 63, v0
	v_lshlrev_b32_e32 v3, 3, v0
	v_bfe_u32 v1, v0, 2, 1
	v_and_b32_e32 v6, 24, v3
	v_mov_b32_e32 v3, s71
	v_mov_b32_e32 v5, s69
	v_cmp_gt_u32_e32 vcc, 48, v58
	v_lshlrev_b32_e32 v4, 6, v1
	v_lshlrev_b32_e32 v176, 8, v1
	v_cndmask_b32_e32 v9, v3, v5, vcc
	v_mov_b32_e32 v3, s70
	v_mov_b32_e32 v5, s68
	v_cmp_eq_u32_e64 s[6:7], 0, v1
	v_xor_b32_e32 v1, 1, v218
	v_cndmask_b32_e32 v8, v3, v5, vcc
	v_cmp_lt_i32_e32 vcc, v1, v219
	v_or_b32_e32 v3, 1, v6
	v_or_b32_e32 v5, 2, v6
	v_cndmask_b32_e32 v1, v218, v1, vcc
	v_lshlrev_b32_e32 v59, 2, v1
	v_xor_b32_e32 v1, 2, v218
	v_cmp_lt_i32_e32 vcc, v1, v219
	v_or_b32_e32 v7, 3, v6
	v_cvt_f32_ubyte0_e32 v3, v3
	v_cndmask_b32_e32 v1, v218, v1, vcc
	v_lshlrev_b32_e32 v60, 2, v1
	v_xor_b32_e32 v1, 4, v218
	v_cmp_lt_i32_e32 vcc, v1, v219
	v_cvt_f32_ubyte0_e32 v5, v5
	v_cvt_f32_ubyte0_e32 v7, v7
	v_cndmask_b32_e32 v1, v218, v1, vcc
	v_lshlrev_b32_e32 v61, 2, v1
	v_cvt_f32_ubyte0_e32 v1, v6
	v_mul_f32_e32 v1, 0xbed49a78, v1
	v_exp_f32_e32 v1, v1
	v_mul_f32_e32 v3, 0xbed49a78, v3
	v_mul_f32_e32 v5, 0xbed49a78, v5
	v_mul_f32_e32 v7, 0xbed49a78, v7
	v_exp_f32_e32 v3, v3
	v_exp_f32_e32 v5, v5
	v_exp_f32_e32 v7, v7
	v_mul_f32_e32 v62, 0.15915494, v1
	v_or_b32_e32 v1, 4, v6
	v_cvt_f32_ubyte0_e32 v1, v1
	v_mul_f32_e32 v1, 0xbed49a78, v1
	v_mul_f32_e32 v63, 0.15915494, v3
	v_mul_f32_e32 v64, 0.15915494, v5
	v_mul_f32_e32 v65, 0.15915494, v7
	v_exp_f32_e32 v1, v1
	v_or_b32_e32 v3, 5, v6
	v_or_b32_e32 v5, 6, v6
	v_or_b32_e32 v7, 7, v6
	v_cvt_f32_ubyte0_e32 v3, v3
	v_cvt_f32_ubyte0_e32 v5, v5
	v_cvt_f32_ubyte0_e32 v7, v7
	v_mul_f32_e32 v3, 0xbed49a78, v3
	v_mul_f32_e32 v5, 0xbed49a78, v5
	v_mul_f32_e32 v7, 0xbed49a78, v7
	s_lshl_b32 s90, s96, 7
	v_exp_f32_e32 v3, v3
	v_exp_f32_e32 v5, v5
	v_exp_f32_e32 v7, v7
	v_lshlrev_b32_e32 v2, 4, v0
	v_lshl_add_u64 v[8:9], s[90:91], 2, v[8:9]
	v_mul_f32_e32 v66, 0.15915494, v1
	v_lshlrev_b32_e32 v1, 5, v0
	v_and_b32_e32 v0, 1, v0
	v_lshl_add_u64 v[8:9], v[8:9], 0, v[176:177]
	v_lshlrev_b32_e32 v176, 2, v6
	v_lshlrev_b32_e32 v0, 4, v0
	s_movk_i32 s3, 0x7c0
	v_readlane_b32 s4, v253, 56
	v_and_b32_e32 v2, 0x380, v2
	v_lshl_add_u64 v[8:9], v[8:9], 0, v[176:177]
	v_and_or_b32 v176, v1, s3, v0
	v_readlane_b32 s5, v253, 57
	v_mul_f32_e32 v67, 0.15915494, v3
	v_mul_f32_e32 v68, 0.15915494, v5
	v_mul_f32_e32 v69, 0.15915494, v7
	v_lshlrev_b32_e32 v70, 3, v58
	v_and_b32_e32 v158, 8, v70
	v_or_b32_e32 v150, 0, v158
	v_cvt_f32_ubyte0_e32 v150, v150
	v_mul_f32_e32 v150, 0xbf549a78, v150
	v_exp_f32_e32 v150, v150
	s_nop 0
	v_mul_f32_e32 v150, 0.15915494, v150
	v_or_b32_e32 v151, 1, v158
	v_cvt_f32_ubyte0_e32 v151, v151
	v_mul_f32_e32 v151, 0xbf549a78, v151
	v_exp_f32_e32 v151, v151
	s_nop 0
	v_mul_f32_e32 v151, 0.15915494, v151
	v_or_b32_e32 v152, 2, v158
	v_cvt_f32_ubyte0_e32 v152, v152
	v_mul_f32_e32 v152, 0xbf549a78, v152
	v_exp_f32_e32 v152, v152
	s_nop 0
	v_mul_f32_e32 v152, 0.15915494, v152
	v_or_b32_e32 v153, 3, v158
	v_cvt_f32_ubyte0_e32 v153, v153
	v_mul_f32_e32 v153, 0xbf549a78, v153
	v_exp_f32_e32 v153, v153
	s_nop 0
	v_mul_f32_e32 v153, 0.15915494, v153
	v_or_b32_e32 v154, 4, v158
	v_cvt_f32_ubyte0_e32 v154, v154
	v_mul_f32_e32 v154, 0xbf549a78, v154
	v_exp_f32_e32 v154, v154
	s_nop 0
	v_mul_f32_e32 v154, 0.15915494, v154
	v_or_b32_e32 v155, 5, v158
	v_cvt_f32_ubyte0_e32 v155, v155
	v_mul_f32_e32 v155, 0xbf549a78, v155
	v_exp_f32_e32 v155, v155
	s_nop 0
	v_mul_f32_e32 v155, 0.15915494, v155
	v_or_b32_e32 v156, 6, v158
	v_cvt_f32_ubyte0_e32 v156, v156
	v_mul_f32_e32 v156, 0xbf549a78, v156
	v_exp_f32_e32 v156, v156
	s_nop 0
	v_mul_f32_e32 v156, 0.15915494, v156
	v_or_b32_e32 v157, 7, v158
	v_cvt_f32_ubyte0_e32 v157, v157
	v_mul_f32_e32 v157, 0xbf549a78, v157
	v_exp_f32_e32 v157, v157
	s_nop 0
	v_mul_f32_e32 v157, 0.15915494, v157
	v_lshl_add_u64 v[10:11], s[4:5], 0, v[176:177]
	v_lshlrev_b32_e32 v176, 1, v2
	v_lshlrev_b32_e32 v12, 1, v4
	v_lshlrev_b32_e32 v14, 1, v6
	global_load_dword v134, v[8:9], off offset:128
	global_load_dword v135, v[8:9], off offset:4
	global_load_dword v136, v[8:9], off offset:132
	global_load_dword v137, v[8:9], off offset:8
	global_load_dword v138, v[8:9], off offset:136
	global_load_dword v139, v[8:9], off offset:12
	global_load_dword v140, v[8:9], off offset:140
	global_load_dword v141, v[8:9], off offset:16
	global_load_dword v142, v[8:9], off offset:144
	global_load_dword v143, v[8:9], off offset:20
	global_load_dword v144, v[8:9], off offset:148
	global_load_dword v145, v[8:9], off offset:24
	global_load_dword v146, v[8:9], off offset:152
	global_load_dword v147, v[8:9], off offset:28
	global_load_dword v148, v[8:9], off offset:156
	global_load_dword v149, v[8:9], off offset:0
	s_ashr_i32 s15, s2, 31
	s_mov_b32 s14, s2
	s_lshl_b64 s[14:15], s[14:15], 13
	v_readlane_b32 s20, v253, 56
	v_readlane_b32 s21, v253, 57
	s_add_u32 s20, s20, s14
	s_addc_u32 s21, s21, s15
	v_lshl_add_u64 v[116:117], s[20:21], 0, v[176:177]
	v_mov_b32_e32 v119, v177
	v_mov_b32_e32 v118, v12
	v_lshl_add_u64 v[116:117], v[116:117], 0, v[118:119]
	v_mov_b32_e32 v118, v14
	v_lshl_add_u64 v[116:117], v[116:117], 0, v[118:119]
	s_mov_b64 s[22:23], 0x1600
	v_lshl_add_u64 v[120:121], v[116:117], 0, s[22:23]
	s_mov_b64 s[22:23], 0x1000
	v_lshl_add_u64 v[116:117], v[116:117], 0, s[22:23]
	global_load_dwordx4 v[100:103], v[116:117], off offset:1536
	global_load_dwordx4 v[104:107], v[120:121], off offset:64
	v_lshl_add_u64 v[122:123], v[10:11], 0, s[14:15]
	global_load_dwordx4 v[126:129], v[122:123], off
	global_load_dwordx4 v[130:133], v[122:123], off offset:32
	global_load_dwordx4 v[108:111], v[122:123], off offset:2048
	global_load_dwordx4 v[112:115], v[122:123], off offset:2080
	s_waitcnt vmcnt(0)
	s_branch .LBB0_992

.Lp3_loaded:
	v_cndmask_b32_e32 v22, v25, v24, vcc
	s_mov_b64 s[12:13], 0x800
	v_cmp_lt_u32_e32 vcc, 31, v15
	v_mul_f32_e32 v19, v22, v150
	v_floor_f32_e32 v19, v19
	v_fma_f32 v19, v22, v150, -v19
	v_sin_f32_e32 v18, v19
	v_cos_f32_e32 v20, v19
	v_add_u32_e32 v13, 0x200, v13
	s_or_b64 s[10:11], vcc, s[10:11]
	v_mul_f32_e32 v21, v22, v151
	v_floor_f32_e32 v21, v21
	v_fma_f32 v21, v22, v151, -v21
	v_sin_f32_e32 v19, v21
	v_cos_f32_e32 v21, v21
	v_lshlrev_b32_e32 v26, 16, v4
	v_lshlrev_b32_e32 v28, 16, v0
	v_and_b32_e32 v29, 0xffff0000, v0
	v_and_b32_e32 v27, 0xffff0000, v4
	v_pk_mul_f32 v[30:31], v[20:21], v[28:29]
	s_nop 0
	v_pk_fma_f32 v[30:31], v[18:19], v[26:27], v[30:31]
	v_pk_mul_f32 v[18:19], v[18:19], v[28:29]
	v_lshlrev_b32_e32 v28, 16, v1
	v_pk_fma_f32 v[18:19], v[20:21], v[26:27], v[18:19] neg_lo:[0,0,1] neg_hi:[0,0,1]
	v_and_b32_e32 v29, 0xffff0000, v1
	v_cvt_pk_bf16_f32 v4, v18, v19
	v_cvt_pk_bf16_f32 v0, v30, v31
	v_lshlrev_b32_e32 v26, 16, v5
	v_and_b32_e32 v27, 0xffff0000, v5
	v_mul_f32_e32 v19, v22, v152
	v_floor_f32_e32 v19, v19
	v_fma_f32 v19, v22, v152, -v19
	v_sin_f32_e32 v18, v19
	v_cos_f32_e32 v20, v19
	s_nop 0
	v_mul_f32_e32 v21, v22, v153
	v_floor_f32_e32 v21, v21
	v_fma_f32 v21, v22, v153, -v21
	v_sin_f32_e32 v19, v21
	v_cos_f32_e32 v21, v21
	s_nop 0
	v_pk_mul_f32 v[30:31], v[20:21], v[28:29]
	s_nop 0
	v_pk_fma_f32 v[30:31], v[18:19], v[26:27], v[30:31]
	v_pk_mul_f32 v[18:19], v[18:19], v[28:29]
	v_lshlrev_b32_e32 v28, 16, v2
	v_pk_fma_f32 v[18:19], v[20:21], v[26:27], v[18:19] neg_lo:[0,0,1] neg_hi:[0,0,1]
	v_and_b32_e32 v29, 0xffff0000, v2
	v_cvt_pk_bf16_f32 v5, v18, v19
	v_cvt_pk_bf16_f32 v1, v30, v31
	v_lshlrev_b32_e32 v26, 16, v6
	v_and_b32_e32 v27, 0xffff0000, v6
	v_mul_f32_e32 v19, v22, v154
	v_floor_f32_e32 v19, v19
	v_fma_f32 v19, v22, v154, -v19
	v_sin_f32_e32 v18, v19
	v_cos_f32_e32 v20, v19
	s_nop 0
	v_mul_f32_e32 v21, v22, v155
	v_floor_f32_e32 v21, v21
	v_fma_f32 v21, v22, v155, -v21
	v_sin_f32_e32 v19, v21
	v_cos_f32_e32 v21, v21
	s_nop 0
	v_pk_mul_f32 v[30:31], v[20:21], v[28:29]
	s_nop 0
	v_pk_fma_f32 v[30:31], v[18:19], v[26:27], v[30:31]
	v_pk_mul_f32 v[18:19], v[18:19], v[28:29]
	v_cvt_pk_bf16_f32 v2, v30, v31
	v_pk_fma_f32 v[18:19], v[20:21], v[26:27], v[18:19] neg_lo:[0,0,1] neg_hi:[0,0,1]
	v_lshlrev_b32_e32 v26, 16, v3
	v_cvt_pk_bf16_f32 v6, v18, v19
	v_and_b32_e32 v27, 0xffff0000, v3
	v_mul_f32_e32 v19, v22, v156
	v_floor_f32_e32 v19, v19
	v_fma_f32 v19, v22, v156, -v19
	v_sin_f32_e32 v18, v19
	v_cos_f32_e32 v20, v19
	v_and_b32_e32 v23, 0xffff0000, v7
	v_mul_f32_e32 v21, v22, v157
	v_floor_f32_e32 v21, v21
	v_fma_f32 v21, v22, v157, -v21
	v_sin_f32_e32 v19, v21
	v_cos_f32_e32 v21, v21
	v_lshlrev_b32_e32 v22, 16, v7
	v_pk_mul_f32 v[28:29], v[20:21], v[26:27]
	s_nop 0
	v_pk_fma_f32 v[28:29], v[18:19], v[22:23], v[28:29]
	v_pk_mul_f32 v[18:19], v[18:19], v[26:27]
	v_cvt_pk_bf16_f32 v3, v28, v29
	v_pk_fma_f32 v[18:19], v[20:21], v[22:23], v[18:19] neg_lo:[0,0,1] neg_hi:[0,0,1]
	s_nop 0
	v_cvt_pk_bf16_f32 v7, v18, v19
	global_store_dwordx4 v[16:17], v[4:7], off sc1
	global_store_dwordx4 v[16:17], v[0:3], off offset:32 sc1
	v_lshl_add_u64 v[16:17], v[16:17], 0, s[12:13]
	s_nop 0
	v_add_u32_e32 v0, 64, v15
	v_mov_b32_e32 v15, v0
	s_andn2_b64 exec, exec, s[10:11]
	s_cbranch_execnz .LBB0_994
	s_or_b64 exec, exec, s[10:11]
